# differential attention tile loop hand-scheduled: key-half split, bias/exp/cvt interleaved under PV MFMAs, V fragments streamed through 8 register slots, in-place P packing
# speedup vs baseline: 1.0622x; 1.0207x over previous
; #define SLOADD(k0) do { s_kn = *reinterpret_cast<const bf16x8*>(Kn + (size_t)((k0) + kn_r) * 1024 + kn_c); s_v0 = *reinterpret_cast<const bf16x8*>(Vh + (size_t)((k0) + v4_r) * 1024 + v4_c); \
;     s_v1 = *reinterpret_cast<const bf16x8*>(Vh + (size_t)((k0) + 32 + v4_r) * 1024 + v4_c); s_pk = (float)posk[(k0) + (tid & 63)]; } while (0)
; __device__ __forceinline__ void attn_diff1(const bf16* __restrict__ Qrow, const bf16* __restrict__ Kn, const bf16* __restrict__ Vh, const int* __restrict__ posk, const float pq, const float cneg, ...
;     ...
;         const char* buf = lds + cur;
;         f32x16 p0 = f32x16{}, p1 = f32x16{};
;         {   const char* kb = buf + KN_OFF + r32 * 144 + hi * 16;
;             bf16x8 c0 = *reinterpret_cast<const bf16x8*>(kb), c1 = *reinterpret_cast<const bf16x8*>(kb + 32 * 144);
; #pragma unroll
;             for (int d0 = 0; d0 < 4; ++d0) {
;                 bf16x8 n0 = c0, n1 = c1;
;                 if (d0 + 1 < 4) { n0 = *reinterpret_cast<const bf16x8*>(kb + (d0 + 1) * 32); n1 = *reinterpret_cast<const bf16x8*>(kb + 32 * 144 + (d0 + 1) * 32); }
;                 p0 = __builtin_amdgcn_mfma_f32_32x32x16_bf16(c0, qr[d0], p0, 0, 0, 0); p1 = __builtin_amdgcn_mfma_f32_32x32x16_bf16(c1, qr[d0], p1, 0, 0, 0);
;                 c0 = n0; c1 = n1;
;             }
;         }
;         if (t + 1 < NT) SLOADD((t0 + t + 1) * 64);
;         const int vb = vb0 + cur;
;     ...
;         s16x4 la[4], ha[4], lb[4], hb[4];
;         VRD(0, la, ha); VRD(1, lb, hb);
;         {   const char* pkl = buf + PK_OFF;
; #pragma unroll
;             for (int i = 0; i < 4; ++i) {
;                 const f32x4 k0 = *(const f32x4*)(pkl + (8 * i + 4 * hi) * 4), k1 = *(const f32x4*)(pkl + (32 + 8 * i + 4 * hi) * 4);
; #pragma unroll
;                 for (int q = 0; q < 4; ++q) { p0[4 * i + q] = fmaf(fabsf(pq - k0[q]), cneg, p0[4 * i + q]); p1[4 * i + q] = fmaf(fabsf(pq - k1[q]), cneg, p1[4 * i + q]); }
;             }
;         }
;         bf16x8 fa0, fa1, fa2, fa3;
;         {   float ps = 0.f;
; #pragma unroll
;             for (int r = 0; r < 16; ++r) { p0[r] = __builtin_amdgcn_exp2f(p0[r]); p1[r] = __builtin_amdgcn_exp2f(p1[r]);     ps += p0[r] + p1[r]; }
;             l_reg += ps; PK4(p0, 0, fa0); PK4(p0, 8, fa1); PK4(p1, 0, fa2); PK4(p1, 8, fa3); }
.LBB0_531:
	s_mov_b32 s70, s45
	v_add3_u32 v229, s70, v225, v226
	ds_read_b128 v[124:127], v229
	ds_read_b128 v[128:131], v229 offset:32
	ds_read_b128 v[132:135], v229 offset:64
	ds_read_b128 v[136:139], v229 offset:96
	ds_read_b128 v[140:143], v229 offset:4608
	ds_read_b128 v[144:147], v229 offset:4640
	ds_read_b128 v[148:151], v229 offset:4672
	ds_read_b128 v[152:155], v229 offset:4704
	v_add_u32_e32 v211, s70, v226
	ds_read_b128 v[186:189], v211 offset:30720
	ds_read_b128 v[230:233], v211 offset:30752
	ds_read_b128 v[234:237], v211 offset:30784
	ds_read_b128 v[242:245], v211 offset:30816
	s_cmp_lt_i32 s69, s35
	s_cselect_b64 s[16:17], -1, 0
	s_cmp_ge_i32 s69, s35
	s_waitcnt vmcnt(0)
	s_cbranch_scc1 .Ld1_skipld
	v_subrev_u32_e32 v106, 32, v206
	v_ashrrev_i32_e32 v211, 31, v210
	v_ashrrev_i32_e32 v107, 31, v106
	v_lshlrev_b64 v[104:105], 11, v[210:211]
	v_lshlrev_b64 v[106:107], 11, v[106:107]
	v_ashrrev_i32_e32 v209, 31, v208
	v_lshl_add_u64 v[104:105], v[202:203], 0, v[104:105]
	v_lshl_add_u64 v[108:109], v[204:205], 0, v[106:107]
	v_lshl_add_u64 v[94:95], v[208:209], 2, v[196:197]
	global_load_dwordx4 v[104:107], v[104:105], off
	s_nop 0
	global_load_dwordx4 v[108:111], v[108:109], off
	v_ashrrev_i32_e32 v207, 31, v206
	v_lshlrev_b64 v[120:121], 11, v[206:207]
	v_lshl_add_u64 v[120:121], v[204:205], 0, v[120:121]
	global_load_dwordx4 v[120:123], v[120:121], off
	s_nop 0
	global_load_dword v207, v[94:95], off
.Ld1_skipld:
	v_add_u32_e32 v209, s45, v228
	s_waitcnt lgkmcnt(11)
	v_mfma_f32_32x32x16_bf16 v[64:79], v[124:127], v[96:99], 0
	s_waitcnt lgkmcnt(10)
	v_mfma_f32_32x32x16_bf16 v[64:79], v[128:131], v[100:103], v[64:79]
	s_waitcnt lgkmcnt(9)
	v_mfma_f32_32x32x16_bf16 v[64:79], v[132:135], v[112:115], v[64:79]
	s_waitcnt lgkmcnt(8)
	v_mfma_f32_32x32x16_bf16 v[64:79], v[136:139], v[116:119], v[64:79]
	ds_read_b64_tr_b16 v[124:125], v209
	ds_read_b64_tr_b16 v[126:127], v209 offset:2048
	ds_read_b64_tr_b16 v[128:129], v209 offset:512
	ds_read_b64_tr_b16 v[130:131], v209 offset:2560
	ds_read_b64_tr_b16 v[132:133], v209 offset:1024
	ds_read_b64_tr_b16 v[134:135], v209 offset:3072
	ds_read_b64_tr_b16 v[136:137], v209 offset:1536
	ds_read_b64_tr_b16 v[138:139], v209 offset:3584
	s_waitcnt lgkmcnt(8)
	v_sub_f32_e32 v186, v168, v186
	v_sub_f32_e32 v187, v168, v187
	v_sub_f32_e32 v188, v168, v188
	v_sub_f32_e32 v189, v168, v189
	s_waitcnt lgkmcnt(15)
	v_mfma_f32_32x32x16_bf16 v[80:95], v[140:143], v[96:99], 0
	v_sub_f32_e32 v230, v168, v230
	v_sub_f32_e32 v231, v168, v231
	v_sub_f32_e32 v232, v168, v232
	v_sub_f32_e32 v233, v168, v233
	s_waitcnt lgkmcnt(14)
	v_mfma_f32_32x32x16_bf16 v[80:95], v[144:147], v[100:103], v[80:95]
	v_sub_f32_e32 v234, v168, v234
	v_sub_f32_e32 v235, v168, v235
	v_sub_f32_e32 v236, v168, v236
	v_sub_f32_e32 v237, v168, v237
	s_waitcnt lgkmcnt(13)
	v_mfma_f32_32x32x16_bf16 v[80:95], v[148:151], v[112:115], v[80:95]
	v_sub_f32_e32 v242, v168, v242
	v_sub_f32_e32 v243, v168, v243
	v_sub_f32_e32 v244, v168, v244
	v_sub_f32_e32 v245, v168, v245
	s_waitcnt lgkmcnt(12)
	v_mfma_f32_32x32x16_bf16 v[80:95], v[152:155], v[116:119], v[80:95]
	ds_read_b64_tr_b16 v[140:141], v209 offset:4096
	ds_read_b64_tr_b16 v[142:143], v209 offset:6144
	ds_read_b64_tr_b16 v[144:145], v209 offset:4608
	ds_read_b64_tr_b16 v[146:147], v209 offset:6656
	ds_read_b64_tr_b16 v[148:149], v209 offset:5120
	ds_read_b64_tr_b16 v[150:151], v209 offset:7168
	ds_read_b64_tr_b16 v[152:153], v209 offset:5632
	ds_read_b64_tr_b16 v[154:155], v209 offset:7680
	v_fma_f32 v64, |v186|, -v165, v64
	v_fma_f32 v65, |v187|, -v165, v65
	v_fma_f32 v66, |v188|, -v165, v66
	v_fma_f32 v67, |v189|, -v165, v67
	v_fma_f32 v68, |v230|, -v165, v68
	v_fma_f32 v69, |v231|, -v165, v69
	v_fma_f32 v70, |v232|, -v165, v70
	v_fma_f32 v71, |v233|, -v165, v71
	v_fma_f32 v72, |v234|, -v165, v72
	v_fma_f32 v73, |v235|, -v165, v73
	v_fma_f32 v74, |v236|, -v165, v74
	v_fma_f32 v75, |v237|, -v165, v75
	v_fma_f32 v76, |v242|, -v165, v76
	v_fma_f32 v77, |v243|, -v165, v77
	v_fma_f32 v78, |v244|, -v165, v78
	v_fma_f32 v79, |v245|, -v165, v79
	v_add_u32_e32 v211, s70, v226
	ds_read_b128 v[186:189], v211 offset:30848
	ds_read_b128 v[230:233], v211 offset:30880
	ds_read_b128 v[234:237], v211 offset:30912
	ds_read_b128 v[242:245], v211 offset:30944
	v_exp_f32_e32 v64, v64
	v_exp_f32_e32 v65, v65
	v_add_f32_e32 v184, v184, v64
	v_exp_f32_e32 v66, v66
	v_add_f32_e32 v184, v184, v65
	v_exp_f32_e32 v67, v67
	v_add_f32_e32 v184, v184, v66
	v_exp_f32_e32 v68, v68
	v_add_f32_e32 v184, v184, v67
	v_exp_f32_e32 v69, v69
	v_add_f32_e32 v184, v184, v68
	v_exp_f32_e32 v70, v70
	v_add_f32_e32 v184, v184, v69
	v_exp_f32_e32 v71, v71
	v_add_f32_e32 v184, v184, v70
	v_exp_f32_e32 v72, v72
	v_add_f32_e32 v184, v184, v71
	v_exp_f32_e32 v73, v73
	v_add_f32_e32 v184, v184, v72
	v_exp_f32_e32 v74, v74
	v_add_f32_e32 v184, v184, v73
	v_exp_f32_e32 v75, v75
	v_add_f32_e32 v184, v184, v74
	v_exp_f32_e32 v76, v76
	v_add_f32_e32 v184, v184, v75
	v_exp_f32_e32 v77, v77
	v_add_f32_e32 v184, v184, v76
	v_exp_f32_e32 v78, v78
	v_add_f32_e32 v184, v184, v77
	v_exp_f32_e32 v79, v79
	v_add_f32_e32 v184, v184, v78
	v_add_f32_e32 v184, v184, v79
	v_cvt_pk_bf16_f32 v64, v64, v65
	v_cvt_pk_bf16_f32 v65, v66, v67
	v_cvt_pk_bf16_f32 v66, v68, v69
	v_cvt_pk_bf16_f32 v67, v70, v71
	v_cvt_pk_bf16_f32 v68, v72, v73
	v_cvt_pk_bf16_f32 v69, v74, v75
	v_cvt_pk_bf16_f32 v70, v76, v77
	v_cvt_pk_bf16_f32 v71, v78, v79
	s_nop 1
	v_permlane32_swap_b32_e32 v64, v66
	v_permlane32_swap_b32_e32 v65, v67
	v_permlane32_swap_b32_e32 v68, v70
	v_permlane32_swap_b32_e32 v69, v71
	s_waitcnt lgkmcnt(15)
; #define SBAR() __builtin_amdgcn_sched_barrier(0)
; #define SWRITED(boff) do { char* bb_ = lds + (boff); *reinterpret_cast<bf16x8*>(bb_ + KN_OFF + kn_st) = s_kn; *reinterpret_cast<bf16x8*>(bb_ + V_OFF + vst0) = s_v0; \
;     *reinterpret_cast<bf16x8*>(bb_ + V_OFF + vst1) = s_v1; if (tid < 64) *reinterpret_cast<float*>(bb_ + PK_OFF + tid * 4) = s_pk; } while (0)
; #define VRD(D0, L, H) do { constexpr int KS = 2 * 4 * 512, HF = 4 * 512, B0 = (D0) * 512; \
;             L[0] = tr_read<B0>(vb); H[0] = tr_read<B0 + HF>(vb); L[1] = tr_read<B0 + KS>(vb); H[1] = tr_read<B0 + KS + HF>(vb); \
;             L[2] = tr_read<B0 + 2 * KS>(vb); H[2] = tr_read<B0 + 2 * KS + HF>(vb); L[3] = tr_read<B0 + 3 * KS>(vb); H[3] = tr_read<B0 + 3 * KS + HF>(vb); } while (0)
; __device__ __forceinline__ void attn_diff1(const bf16* __restrict__ Qrow, const bf16* __restrict__ Kn, const bf16* __restrict__ Vh, const int* __restrict__ posk, const float pq, const float cneg, ...
;     ...
;         s16x4 la[4], ha[4], lb[4], hb[4];
;         VRD(0, la, ha); VRD(1, lb, hb);
;         {   const char* pkl = buf + PK_OFF;
; #pragma unroll
;             for (int i = 0; i < 4; ++i) {
;                 const f32x4 k0 = *(const f32x4*)(pkl + (8 * i + 4 * hi) * 4), k1 = *(const f32x4*)(pkl + (32 + 8 * i + 4 * hi) * 4);
; #pragma unroll
;                 for (int q = 0; q < 4; ++q) { p0[4 * i + q] = fmaf(fabsf(pq - k0[q]), cneg, p0[4 * i + q]); p1[4 * i + q] = fmaf(fabsf(pq - k1[q]), cneg, p1[4 * i + q]); }
;             }
;         }
;         bf16x8 fa0, fa1, fa2, fa3;
;         {   float ps = 0.f;
; #pragma unroll
;             for (int r = 0; r < 16; ++r) { p0[r] = __builtin_amdgcn_exp2f(p0[r]); p1[r] = __builtin_amdgcn_exp2f(p1[r]);     ps += p0[r] + p1[r]; }
;             l_reg += ps; PK4(p0, 0, fa0); PK4(p0, 8, fa1); PK4(p1, 0, fa2); PK4(p1, 8, fa3); }
;         asm volatile("s_waitcnt lgkmcnt(0)" ::: "memory"); SBAR();
;         PVM(0, la, ha); SBAR();
;         VRD(2, la, ha);
;         SBAR(); PVM(1, lb, hb); SBAR();
;         VRD(3, lb, hb);
;         asm volatile("s_waitcnt lgkmcnt(8)" ::: "memory"); SBAR();
;         PVM(2, la, ha);
;         asm volatile("s_waitcnt lgkmcnt(0)" ::: "memory"); SBAR();
;         PVM(3, lb, hb);
;     ...
;         if (t + 1 < NT) SWRITED(BUF - cur);
	v_mfma_f32_32x32x16_bf16 v[48:63], v[64:67], v[124:127], v[48:63]
	ds_read_b64_tr_b16 v[124:125], v209 offset:8192
	ds_read_b64_tr_b16 v[126:127], v209 offset:10240
	s_waitcnt lgkmcnt(2)
	v_sub_f32_e32 v186, v168, v186
	v_sub_f32_e32 v187, v168, v187
	v_sub_f32_e32 v188, v168, v188
	v_sub_f32_e32 v189, v168, v189
	v_sub_f32_e32 v230, v168, v230
	v_sub_f32_e32 v231, v168, v231
	v_sub_f32_e32 v232, v168, v232
	v_sub_f32_e32 v233, v168, v233
	s_waitcnt lgkmcnt(15)
	v_mfma_f32_32x32x16_bf16 v[32:47], v[64:67], v[128:131], v[32:47]
	ds_read_b64_tr_b16 v[128:129], v209 offset:8704
	ds_read_b64_tr_b16 v[130:131], v209 offset:10752
	v_sub_f32_e32 v234, v168, v234
	v_sub_f32_e32 v235, v168, v235
	v_sub_f32_e32 v236, v168, v236
	v_sub_f32_e32 v237, v168, v237
	v_sub_f32_e32 v242, v168, v242
	v_sub_f32_e32 v243, v168, v243
	v_sub_f32_e32 v244, v168, v244
	v_sub_f32_e32 v245, v168, v245
	v_fma_f32 v80, |v186|, -v165, v80
	v_fma_f32 v81, |v187|, -v165, v81
	s_waitcnt lgkmcnt(15)
	v_mfma_f32_32x32x16_bf16 v[16:31], v[64:67], v[132:135], v[16:31]
	ds_read_b64_tr_b16 v[132:133], v209 offset:9216
	ds_read_b64_tr_b16 v[134:135], v209 offset:11264
	v_fma_f32 v82, |v188|, -v165, v82
	v_fma_f32 v83, |v189|, -v165, v83
	v_fma_f32 v84, |v230|, -v165, v84
	v_fma_f32 v85, |v231|, -v165, v85
	v_fma_f32 v86, |v232|, -v165, v86
	v_fma_f32 v87, |v233|, -v165, v87
	v_fma_f32 v88, |v234|, -v165, v88
	v_fma_f32 v89, |v235|, -v165, v89
	v_fma_f32 v90, |v236|, -v165, v90
	v_fma_f32 v91, |v237|, -v165, v91
	s_waitcnt lgkmcnt(15)
	v_mfma_f32_32x32x16_bf16 v[0:15], v[64:67], v[136:139], v[0:15]
	ds_read_b64_tr_b16 v[136:137], v209 offset:9728
	ds_read_b64_tr_b16 v[138:139], v209 offset:11776
	v_fma_f32 v92, |v242|, -v165, v92
	v_fma_f32 v93, |v243|, -v165, v93
	v_fma_f32 v94, |v244|, -v165, v94
	v_fma_f32 v95, |v245|, -v165, v95
	v_exp_f32_e32 v80, v80
	v_exp_f32_e32 v81, v81
	v_add_f32_e32 v184, v184, v80
	v_exp_f32_e32 v82, v82
	v_add_f32_e32 v184, v184, v81
	v_exp_f32_e32 v83, v83
	s_waitcnt lgkmcnt(15)
	v_mfma_f32_32x32x16_bf16 v[48:63], v[68:71], v[140:143], v[48:63]
	ds_read_b64_tr_b16 v[140:141], v209 offset:12288
	ds_read_b64_tr_b16 v[142:143], v209 offset:14336
	v_add_f32_e32 v184, v184, v82
	v_exp_f32_e32 v84, v84
	v_add_f32_e32 v184, v184, v83
	v_exp_f32_e32 v85, v85
	v_add_f32_e32 v184, v184, v84
	v_exp_f32_e32 v86, v86
	v_add_f32_e32 v184, v184, v85
	v_exp_f32_e32 v87, v87
	v_add_f32_e32 v184, v184, v86
	v_exp_f32_e32 v88, v88
	s_waitcnt lgkmcnt(15)
	v_mfma_f32_32x32x16_bf16 v[32:47], v[68:71], v[144:147], v[32:47]
	ds_read_b64_tr_b16 v[144:145], v209 offset:12800
	ds_read_b64_tr_b16 v[146:147], v209 offset:14848
	v_add_f32_e32 v184, v184, v87
	v_exp_f32_e32 v89, v89
	v_add_f32_e32 v184, v184, v88
	v_exp_f32_e32 v90, v90
	v_add_f32_e32 v184, v184, v89
	v_exp_f32_e32 v91, v91
	v_add_f32_e32 v184, v184, v90
	v_exp_f32_e32 v92, v92
	v_add_f32_e32 v184, v184, v91
	v_exp_f32_e32 v93, v93
	s_waitcnt lgkmcnt(15)
	v_mfma_f32_32x32x16_bf16 v[16:31], v[68:71], v[148:151], v[16:31]
	ds_read_b64_tr_b16 v[148:149], v209 offset:13312
	ds_read_b64_tr_b16 v[150:151], v209 offset:15360
	v_add_f32_e32 v184, v184, v92
	v_exp_f32_e32 v94, v94
	v_add_f32_e32 v184, v184, v93
	v_exp_f32_e32 v95, v95
	v_add_f32_e32 v184, v184, v94
	v_add_f32_e32 v184, v184, v95
	v_cvt_pk_bf16_f32 v80, v80, v81
	v_cvt_pk_bf16_f32 v81, v82, v83
	v_cvt_pk_bf16_f32 v82, v84, v85
	v_cvt_pk_bf16_f32 v83, v86, v87
	s_waitcnt lgkmcnt(15)
	v_mfma_f32_32x32x16_bf16 v[0:15], v[68:71], v[152:155], v[0:15]
	ds_read_b64_tr_b16 v[152:153], v209 offset:13824
	ds_read_b64_tr_b16 v[154:155], v209 offset:15872
	v_cvt_pk_bf16_f32 v84, v88, v89
	v_cvt_pk_bf16_f32 v85, v90, v91
	v_cvt_pk_bf16_f32 v86, v92, v93
	v_cvt_pk_bf16_f32 v87, v94, v95
	s_nop 1
	v_permlane32_swap_b32_e32 v80, v82
	v_permlane32_swap_b32_e32 v81, v83
	v_permlane32_swap_b32_e32 v84, v86
	v_permlane32_swap_b32_e32 v85, v87
	s_waitcnt lgkmcnt(14)
	v_mfma_f32_32x32x16_bf16 v[48:63], v[80:83], v[124:127], v[48:63]
	s_waitcnt lgkmcnt(12)
	v_mfma_f32_32x32x16_bf16 v[32:47], v[80:83], v[128:131], v[32:47]
	s_waitcnt lgkmcnt(10)
	v_mfma_f32_32x32x16_bf16 v[16:31], v[80:83], v[132:135], v[16:31]
	s_waitcnt lgkmcnt(8)
	v_mfma_f32_32x32x16_bf16 v[0:15], v[80:83], v[136:139], v[0:15]
	s_andn2_b64 vcc, exec, s[16:17]
	s_cbranch_vccnz .Ld1_nostage
	s_sub_i32 s70, 0, s45
	v_add_u32_e32 v229, s70, v164
	s_waitcnt vmcnt(0)
	ds_write_b128 v229, v[104:107] offset:30976
	v_add_u32_e32 v229, s70, v219
	ds_write_b128 v229, v[108:111] offset:45312
	v_add_u32_e32 v229, s70, v220
	v_cvt_f32_i32_e32 v207, v207
	ds_write_b128 v229, v[120:123] offset:45312
	s_and_saveexec_b64 s[16:17], s[42:43]
	s_cbranch_execz .Ld1_stg_done
	v_add_u32_e32 v229, s70, v227
	ds_write_b32 v229, v207 offset:61696

; #define SBAR() __builtin_amdgcn_sched_barrier(0)
; #define SWRITED(boff) do { char* bb_ = lds + (boff); *reinterpret_cast<bf16x8*>(bb_ + KN_OFF + kn_st) = s_kn; *reinterpret_cast<bf16x8*>(bb_ + V_OFF + vst0) = s_v0; \
;     *reinterpret_cast<bf16x8*>(bb_ + V_OFF + vst1) = s_v1; if (tid < 64) *reinterpret_cast<float*>(bb_ + PK_OFF + tid * 4) = s_pk; } while (0)
; #define VRD(D0, L, H) do { constexpr int KS = 2 * 4 * 512, HF = 4 * 512, B0 = (D0) * 512; \
;             L[0] = tr_read<B0>(vb); H[0] = tr_read<B0 + HF>(vb); L[1] = tr_read<B0 + KS>(vb); H[1] = tr_read<B0 + KS + HF>(vb); \
;             L[2] = tr_read<B0 + 2 * KS>(vb); H[2] = tr_read<B0 + 2 * KS + HF>(vb); L[3] = tr_read<B0 + 3 * KS>(vb); H[3] = tr_read<B0 + 3 * KS + HF>(vb); } while (0)
; #define PVM(D0, L, H) do { o[D0] = __builtin_amdgcn_mfma_f32_32x32x16_bf16(fa0, VFR(L, H, 0), o[D0], 0, 0, 0); o[D0] = __builtin_amdgcn_mfma_f32_32x32x16_bf16(fa1, VFR(L, H, 1), o[D0], 0, 0, 0); \
;             o[D0] = __builtin_amdgcn_mfma_f32_32x32x16_bf16(fa2, VFR(L, H, 2), o[D0], 0, 0, 0); o[D0] = __builtin_amdgcn_mfma_f32_32x32x16_bf16(fa3, VFR(L, H, 3), o[D0], 0, 0, 0); } while (0)
; __device__ __forceinline__ void attn_diff1(const bf16* __restrict__ Qrow, const bf16* __restrict__ Kn, const bf16* __restrict__ Vh, const int* __restrict__ posk, const float pq, const float cneg, ...
;     ...
;         asm volatile("s_waitcnt lgkmcnt(0)" ::: "memory"); SBAR();
;         PVM(0, la, ha); SBAR();
;         VRD(2, la, ha);
;         SBAR(); PVM(1, lb, hb); SBAR();
;         VRD(3, lb, hb);
;         asm volatile("s_waitcnt lgkmcnt(8)" ::: "memory"); SBAR();
;         PVM(2, la, ha);
;         asm volatile("s_waitcnt lgkmcnt(0)" ::: "memory"); SBAR();
;         PVM(3, lb, hb);
;     ...
;         if (t + 1 < NT) SWRITED(BUF - cur);
;         __syncthreads();
;         cur = BUF - cur;
;     }
.Ld1_nostage:
	s_waitcnt lgkmcnt(0)
	v_mfma_f32_32x32x16_bf16 v[48:63], v[84:87], v[140:143], v[48:63]
	v_mfma_f32_32x32x16_bf16 v[32:47], v[84:87], v[144:147], v[32:47]
	v_mfma_f32_32x32x16_bf16 v[16:31], v[84:87], v[148:151], v[16:31]
	v_mfma_f32_32x32x16_bf16 v[0:15], v[84:87], v[152:155], v[0:15]
	s_sub_i32 s45, 0x7900, s45
	s_add_i32 s69, s69, 1
	v_add_u32_e32 v206, 64, v206
	v_add_u32_e32 v208, 64, v208
	v_add_u32_e32 v210, 64, v210
	s_cmp_eq_u32 s54, s69
	s_waitcnt lgkmcnt(0)
	s_barrier
	s_cbranch_scc1 .LBB0_537
	s_branch .LBB0_531
